# attention pair jobs: accumulator addresses and accumulator loads moved from behind the score phase into its last eight K steps
# baseline (speedup 1.0000x reference)
.Latt_unit:
	s_add_i32 s92, s11, s66
	s_cmpk_lt_u32 s92, 0x900
	s_cselect_b32 s92, s92, s11
	s_mul_hi_u32 s45, s92, 0xaaaaaaab
	s_lshr_b32 s45, s45, 7
	s_mul_i32 s90, s45, 0xc0
	s_sub_i32 s90, s92, s90
	s_lshl_b32 s44, s90, 8
	s_cmp_lt_u32 s90, 64
	s_mov_b32 s91, 0x7fffc000
	s_cselect_b32 s91, 0xfffff800, s91
	s_movk_i32 s41, 0x3fff
	s_cselect_b32 s41, 0x7ff, s41
	s_and_b32 s91, s91, s44
	s_sub_i32 s39, s44, s91
	s_mul_i32 s90, s45, 0x600000
	s_lshl_b32 s91, s91, 7
	s_add_u32 s90, s90, s91
	s_add_u32 s30, s46, 0x9800000
	s_addc_u32 s31, s47, 0
	s_add_u32 s30, s30, s90
	s_addc_u32 s31, s31, 0
	s_add_u32 s34, s46, 0xe000000
	s_addc_u32 s35, s47, 0
	s_add_u32 s34, s34, s90
	s_addc_u32 s35, s35, 0
	s_add_u32 s36, s46, 0x12800000
	s_addc_u32 s37, s47, 0
	s_add_u32 s36, s36, s90
	s_addc_u32 s37, s37, 0
	s_add_i32 s76, s38, s82
	s_add_i32 s79, s38, s83
	v_lshlrev_b32_e32 v231, 0, v218
	v_add_u32_e32 v232, 8, v218
	v_lshlrev_b32_e32 v232, 0, v232
	v_lshlrev_b32_e32 v162, 2, v218
	v_add_u32_e32 v163, 8, v218
	v_lshlrev_b32_e32 v163, 2, v163
	s_waitcnt vmcnt(8)
	v_add_u32_e32 v154, s12, v223
	v_add_u32_e32 v155, s12, v224
	ds_read_b128 v[72:75], v154
	ds_read_b128 v[76:79], v155
	s_waitcnt lgkmcnt(0)
	s_add_i32 s93, s76, -16
	s_mov_b32 m0, s12
	v_add_u32_e32 v164, s93, v231
	v_med3_i32 v164, v164, 0, s40
	v_lshl_or_b32 v164, v164, 7, v220
	global_load_lds_dwordx4 v164, s[20:21]
	s_add_i32 m0, s12, 0x400
	v_add_u32_e32 v165, s93, v232
	v_med3_i32 v165, v165, 0, s40
	v_lshl_or_b32 v165, v165, 7, v221
	global_load_lds_dwordx4 v165, s[20:21]
	s_waitcnt vmcnt(8)
	v_add_u32_e32 v154, s13, v223
	v_add_u32_e32 v155, s13, v224
	ds_read_b128 v[80:83], v154
	ds_read_b128 v[84:87], v155
	s_waitcnt lgkmcnt(0)
	s_add_i32 s93, s76, 0
	s_mov_b32 m0, s13
	v_add_u32_e32 v164, s93, v231
	v_med3_i32 v164, v164, 0, s40
	v_lshl_or_b32 v164, v164, 7, v220
	global_load_lds_dwordx4 v164, s[20:21]
	s_add_i32 m0, s13, 0x400
	v_add_u32_e32 v165, s93, v232
	v_med3_i32 v165, v165, 0, s40
	v_lshl_or_b32 v165, v165, 7, v221
	global_load_lds_dwordx4 v165, s[20:21]
	s_waitcnt vmcnt(8)
	v_add_u32_e32 v154, s14, v223
	v_add_u32_e32 v155, s14, v224
	ds_read_b128 v[88:91], v154
	ds_read_b128 v[92:95], v155
	s_waitcnt lgkmcnt(0)
	s_add_i32 s93, s76, 16
	s_mov_b32 m0, s14
	v_add_u32_e32 v164, s93, v231
	v_med3_i32 v164, v164, 0, s40
	v_lshl_or_b32 v164, v164, 7, v220
	global_load_lds_dwordx4 v164, s[20:21]
	s_add_i32 m0, s14, 0x400
	v_add_u32_e32 v165, s93, v232
	v_med3_i32 v165, v165, 0, s40
	v_lshl_or_b32 v165, v165, 7, v221
	global_load_lds_dwordx4 v165, s[20:21]
	s_waitcnt vmcnt(8)
	v_add_u32_e32 v154, s15, v223
	v_add_u32_e32 v155, s15, v224
	ds_read_b128 v[202:205], v154
	ds_read_b128 v[206:209], v155
	v_mfma_f32_16x16x32_bf16 v[0:3], v[88:91], v[72:75], 0
	v_mfma_f32_16x16x32_bf16 v[0:3], v[92:95], v[76:79], v[0:3]
	s_waitcnt lgkmcnt(0)
	s_add_i32 s93, s76, 32
	s_mov_b32 m0, s15
	v_add_u32_e32 v164, s93, v231
	v_med3_i32 v164, v164, 0, s40
	v_lshl_or_b32 v164, v164, 7, v220
	global_load_lds_dwordx4 v164, s[20:21]
	s_add_i32 m0, s15, 0x400
	v_add_u32_e32 v165, s93, v232
	v_med3_i32 v165, v165, 0, s40
	v_lshl_or_b32 v165, v165, 7, v221
	global_load_lds_dwordx4 v165, s[20:21]
	s_waitcnt vmcnt(8)
	v_add_u32_e32 v154, s16, v223
	v_add_u32_e32 v155, s16, v224
	ds_read_b128 v[88:91], v154
	ds_read_b128 v[92:95], v155
	v_mfma_f32_16x16x32_bf16 v[4:7], v[202:205], v[72:75], 0
	v_mfma_f32_16x16x32_bf16 v[36:39], v[202:205], v[80:83], 0
	v_mfma_f32_16x16x32_bf16 v[4:7], v[206:209], v[76:79], v[4:7]
	v_mfma_f32_16x16x32_bf16 v[36:39], v[206:209], v[84:87], v[36:39]
	s_waitcnt lgkmcnt(0)
	s_add_i32 s93, s76, 48
	s_mov_b32 m0, s16
	v_add_u32_e32 v164, s93, v231
	v_med3_i32 v164, v164, 0, s40
	v_lshl_or_b32 v164, v164, 7, v220
	global_load_lds_dwordx4 v164, s[20:21]
	s_add_i32 m0, s16, 0x400
	v_add_u32_e32 v165, s93, v232
	v_med3_i32 v165, v165, 0, s40
	v_lshl_or_b32 v165, v165, 7, v221
	global_load_lds_dwordx4 v165, s[20:21]
	s_waitcnt vmcnt(8)
	v_add_u32_e32 v154, s12, v223
	v_add_u32_e32 v155, s12, v224
	ds_read_b128 v[202:205], v154
	ds_read_b128 v[206:209], v155
	v_mfma_f32_16x16x32_bf16 v[8:11], v[88:91], v[72:75], 0
	v_mfma_f32_16x16x32_bf16 v[40:43], v[88:91], v[80:83], 0
	v_mfma_f32_16x16x32_bf16 v[8:11], v[92:95], v[76:79], v[8:11]
	v_mfma_f32_16x16x32_bf16 v[40:43], v[92:95], v[84:87], v[40:43]
	v_mov_b32_e32 v188, s82
	v_add_u32_e32 v188, v216, v188
	v_lshrrev_b32_e32 v146, 4, v188
	v_xor_b32_e32 v146, v146, v188
	v_and_b32_e32 v146, 15, v146
	v_lshlrev_b32_e32 v147, 8, v188
	s_waitcnt lgkmcnt(0)
	s_add_i32 s93, s76, 64
	s_mov_b32 m0, s12
	v_add_u32_e32 v164, s93, v231
	v_med3_i32 v164, v164, 0, s40
	v_lshl_or_b32 v164, v164, 7, v220
	global_load_lds_dwordx4 v164, s[20:21]
	s_add_i32 m0, s12, 0x400
	v_add_u32_e32 v165, s93, v232
	v_med3_i32 v165, v165, 0, s40
	v_lshl_or_b32 v165, v165, 7, v221
	global_load_lds_dwordx4 v165, s[20:21]
	s_waitcnt vmcnt(8)
	v_add_u32_e32 v154, s13, v223
	v_add_u32_e32 v155, s13, v224
	ds_read_b128 v[88:91], v154
	ds_read_b128 v[92:95], v155
	v_mfma_f32_16x16x32_bf16 v[12:15], v[202:205], v[72:75], 0
	v_mfma_f32_16x16x32_bf16 v[44:47], v[202:205], v[80:83], 0
	v_mfma_f32_16x16x32_bf16 v[12:15], v[206:209], v[76:79], v[12:15]
	v_mfma_f32_16x16x32_bf16 v[44:47], v[206:209], v[84:87], v[44:47]
	v_or_b32_e32 v148, 0, v217
	v_xor_b32_e32 v148, v148, v146
	v_lshl_add_u32 v190, v148, 4, v147
	v_or_b32_e32 v148, 4, v217
	v_xor_b32_e32 v148, v148, v146
	v_lshl_add_u32 v191, v148, 4, v147
	s_waitcnt lgkmcnt(0)
	s_add_i32 s93, s76, 0x50
	s_mov_b32 m0, s13
	v_add_u32_e32 v164, s93, v231
	v_med3_i32 v164, v164, 0, s40
	v_lshl_or_b32 v164, v164, 7, v220
	global_load_lds_dwordx4 v164, s[20:21]
	s_add_i32 m0, s13, 0x400
	v_add_u32_e32 v165, s93, v232
	v_med3_i32 v165, v165, 0, s40
	v_lshl_or_b32 v165, v165, 7, v221
	global_load_lds_dwordx4 v165, s[20:21]
	s_waitcnt vmcnt(8)
	v_add_u32_e32 v154, s14, v223
	v_add_u32_e32 v155, s14, v224
	ds_read_b128 v[202:205], v154
	ds_read_b128 v[206:209], v155
	v_mfma_f32_16x16x32_bf16 v[16:19], v[88:91], v[72:75], 0
	v_mfma_f32_16x16x32_bf16 v[48:51], v[88:91], v[80:83], 0
	v_mfma_f32_16x16x32_bf16 v[16:19], v[92:95], v[76:79], v[16:19]
	v_mfma_f32_16x16x32_bf16 v[48:51], v[92:95], v[84:87], v[48:51]
	v_or_b32_e32 v148, 8, v217
	v_xor_b32_e32 v148, v148, v146
	v_lshl_add_u32 v192, v148, 4, v147
	v_or_b32_e32 v148, 12, v217
	v_xor_b32_e32 v148, v148, v146
	v_lshl_add_u32 v193, v148, 4, v147
	s_waitcnt lgkmcnt(0)
	s_add_i32 s93, s76, 0xffffffc0
	s_mov_b32 m0, s14
	v_add_u32_e32 v164, s93, v231
	v_med3_i32 v164, v164, 0, s40
	v_lshl_or_b32 v164, v164, 7, v222
	global_load_lds_dwordx4 v164, s[24:25]
	s_add_i32 m0, s14, 0x400
	v_add_u32_e32 v165, s93, v232
	v_med3_i32 v165, v165, 0, s40
	v_lshl_or_b32 v165, v165, 7, v222
	global_load_lds_dwordx4 v165, s[24:25]
	s_waitcnt vmcnt(8)
	v_add_u32_e32 v154, s15, v223
	v_add_u32_e32 v155, s15, v224
	ds_read_b128 v[88:91], v154
	ds_read_b128 v[92:95], v155
	v_mfma_f32_16x16x32_bf16 v[20:23], v[202:205], v[72:75], 0
	v_mfma_f32_16x16x32_bf16 v[52:55], v[202:205], v[80:83], 0
	v_mfma_f32_16x16x32_bf16 v[20:23], v[206:209], v[76:79], v[20:23]
	v_mfma_f32_16x16x32_bf16 v[52:55], v[206:209], v[84:87], v[52:55]
	v_lshlrev_b32_e32 v194, 3, v188
	v_add_u32_e32 v194, 0x10000, v194
	v_mov_b32_e32 v189, s82
	v_add_u32_e32 v189, v216, v189
	v_add_u32_e32 v189, 16, v189
	v_lshrrev_b32_e32 v146, 4, v189
	s_waitcnt lgkmcnt(0)
	s_add_i32 s93, s76, 0xffffffd0
	s_mov_b32 m0, s15
	v_add_u32_e32 v164, s93, v231
	v_med3_i32 v164, v164, 0, s40
	v_lshl_or_b32 v164, v164, 7, v222
	global_load_lds_dwordx4 v164, s[24:25]
	s_add_i32 m0, s15, 0x400
	v_add_u32_e32 v165, s93, v232
	v_med3_i32 v165, v165, 0, s40
	v_lshl_or_b32 v165, v165, 7, v222
	global_load_lds_dwordx4 v165, s[24:25]
	s_waitcnt vmcnt(8)
	v_add_u32_e32 v154, s16, v223
	v_add_u32_e32 v155, s16, v224
	ds_read_b128 v[202:205], v154
	ds_read_b128 v[206:209], v155
	v_mfma_f32_16x16x32_bf16 v[24:27], v[88:91], v[72:75], 0
	v_mfma_f32_16x16x32_bf16 v[56:59], v[88:91], v[80:83], 0
	v_mfma_f32_16x16x32_bf16 v[24:27], v[92:95], v[76:79], v[24:27]
	v_mfma_f32_16x16x32_bf16 v[56:59], v[92:95], v[84:87], v[56:59]
	v_xor_b32_e32 v146, v146, v189
	v_and_b32_e32 v146, 15, v146
	v_lshlrev_b32_e32 v147, 8, v189
	v_or_b32_e32 v148, 0, v217
	v_xor_b32_e32 v148, v148, v146
	v_lshl_add_u32 v195, v148, 4, v147
	s_waitcnt lgkmcnt(0)
	s_add_i32 s93, s76, 0xffffffe0
	s_mov_b32 m0, s16
	v_add_u32_e32 v164, s93, v231
	v_med3_i32 v164, v164, 0, s40
	v_lshl_or_b32 v164, v164, 7, v222
	global_load_lds_dwordx4 v164, s[24:25]
	s_add_i32 m0, s16, 0x400
	v_add_u32_e32 v165, s93, v232
	v_med3_i32 v165, v165, 0, s40
	v_lshl_or_b32 v165, v165, 7, v222
	global_load_lds_dwordx4 v165, s[24:25]
	s_waitcnt vmcnt(8)
	v_add_u32_e32 v154, s12, v223
	v_add_u32_e32 v155, s12, v224
	ds_read_b128 v[88:91], v154
	ds_read_b128 v[92:95], v155
	v_mfma_f32_16x16x32_bf16 v[28:31], v[202:205], v[72:75], 0
	v_mfma_f32_16x16x32_bf16 v[60:63], v[202:205], v[80:83], 0
	v_mfma_f32_16x16x32_bf16 v[28:31], v[206:209], v[76:79], v[28:31]
	v_mfma_f32_16x16x32_bf16 v[60:63], v[206:209], v[84:87], v[60:63]
	v_or_b32_e32 v148, 4, v217
	v_xor_b32_e32 v148, v148, v146
	v_lshl_add_u32 v196, v148, 4, v147
	v_or_b32_e32 v148, 8, v217
	v_xor_b32_e32 v148, v148, v146
	v_lshl_add_u32 v197, v148, 4, v147
	s_waitcnt lgkmcnt(0)
	s_add_i32 s93, s76, -16
	s_mov_b32 m0, s12
	v_add_u32_e32 v164, s93, v231
	v_med3_i32 v164, v164, 0, s40
	v_lshl_or_b32 v164, v164, 7, v222
	global_load_lds_dwordx4 v164, s[24:25]
	s_add_i32 m0, s12, 0x400
	v_add_u32_e32 v165, s93, v232
	v_med3_i32 v165, v165, 0, s40
	v_lshl_or_b32 v165, v165, 7, v222
	global_load_lds_dwordx4 v165, s[24:25]
	s_waitcnt vmcnt(8)
	v_add_u32_e32 v154, s13, v223
	v_add_u32_e32 v155, s13, v224
	ds_read_b128 v[202:205], v154
	ds_read_b128 v[206:209], v155
	v_mfma_f32_16x16x32_bf16 v[32:35], v[88:91], v[72:75], 0
	v_mfma_f32_16x16x32_bf16 v[64:67], v[88:91], v[80:83], 0
	v_mfma_f32_16x16x32_bf16 v[32:35], v[92:95], v[76:79], v[32:35]
	v_mfma_f32_16x16x32_bf16 v[64:67], v[92:95], v[84:87], v[64:67]
	v_or_b32_e32 v148, 12, v217
	v_xor_b32_e32 v148, v148, v146
	v_lshl_add_u32 v198, v148, 4, v147
	v_lshlrev_b32_e32 v199, 3, v189
	v_add_u32_e32 v199, 0x10000, v199
	s_waitcnt lgkmcnt(0)
	s_add_i32 s93, s76, 0
	s_mov_b32 m0, s13
	v_add_u32_e32 v164, s93, v231
	v_med3_i32 v164, v164, 0, s40
	v_lshl_or_b32 v164, v164, 7, v222
	global_load_lds_dwordx4 v164, s[24:25]
	s_add_i32 m0, s13, 0x400
	v_add_u32_e32 v165, s93, v232
	v_med3_i32 v165, v165, 0, s40
	v_lshl_or_b32 v165, v165, 7, v222
	global_load_lds_dwordx4 v165, s[24:25]
	s_waitcnt vmcnt(8)
	v_add_u32_e32 v154, s14, v225
	v_add_u32_e32 v155, s14, v226
	v_add_u32_e32 v156, s14, v227
	v_add_u32_e32 v157, s14, v228
	ds_read_b64_tr_b16 v[88:89], v154
	ds_read_b64_tr_b16 v[90:91], v155
	ds_read_b64_tr_b16 v[92:93], v156
	ds_read_b64_tr_b16 v[94:95], v157
	v_mfma_f32_16x16x32_bf16 v[68:71], v[202:205], v[80:83], 0
	v_mfma_f32_16x16x32_bf16 v[68:71], v[206:209], v[84:87], v[68:71]
	s_add_i32 s90, s76, 0x5f
	s_cmp_gt_i32 s90, s40
	s_cselect_b32 s96, 1, 0
	s_cmp_lt_i32 s76, 64
	s_cselect_b32 s96, 1, s96
	s_ashr_i32 s77, s76, 0
	s_sub_i32 s77, 64, s77
	s_sub_i32 s78, s40, s76
	s_ashr_i32 s78, s78, 0
	s_add_i32 s78, s78, 64
	v_cndmask_b32_e64 v0, v0, v230, s[52:53]
	v_cndmask_b32_e64 v32, v32, v230, s[62:63]
	v_cndmask_b32_e64 v1, v1, v230, s[56:57]
	v_cndmask_b32_e64 v33, v33, v230, s[64:65]
	v_cndmask_b32_e64 v2, v2, v230, s[58:59]
	v_cndmask_b32_e64 v34, v34, v230, s[70:71]
	v_cndmask_b32_e64 v3, v3, v230, s[60:61]
	v_cndmask_b32_e64 v35, v35, v230, s[72:73]
	s_cmp_eq_u32 s96, 0
	s_cbranch_scc1 .Latt_noedge_1
	v_sub_u32_e32 v200, s77, v229
	s_sub_i32 s91, s78, s77
	v_sub_u32_e32 v150, 0, v200
	v_sub_u32_e32 v151, 1, v200
	v_sub_u32_e32 v152, 2, v200
	v_sub_u32_e32 v153, 3, v200
	v_cmp_lt_u32_e64 s[94:95], s91, v150
	v_cmp_lt_u32_e64 s[86:87], s91, v151
	v_cmp_lt_u32_e64 s[0:1], s91, v152
	v_cmp_lt_u32_e64 s[2:3], s91, v153
	v_cndmask_b32_e64 v0, v0, v230, s[94:95]
	v_cndmask_b32_e64 v1, v1, v230, s[86:87]
	v_cndmask_b32_e64 v2, v2, v230, s[0:1]
	v_cndmask_b32_e64 v3, v3, v230, s[2:3]
	v_sub_u32_e32 v150, 16, v200
	v_sub_u32_e32 v151, 17, v200
	v_sub_u32_e32 v152, 18, v200
	v_sub_u32_e32 v153, 19, v200
	v_cmp_lt_u32_e64 s[94:95], s91, v150
	v_cmp_lt_u32_e64 s[86:87], s91, v151
	v_cmp_lt_u32_e64 s[0:1], s91, v152
	v_cmp_lt_u32_e64 s[2:3], s91, v153
	v_cndmask_b32_e64 v4, v4, v230, s[94:95]
	v_cndmask_b32_e64 v5, v5, v230, s[86:87]
	v_cndmask_b32_e64 v6, v6, v230, s[0:1]
	v_cndmask_b32_e64 v7, v7, v230, s[2:3]
	v_sub_u32_e32 v150, 32, v200
	v_sub_u32_e32 v151, 33, v200
	v_sub_u32_e32 v152, 34, v200
	v_sub_u32_e32 v153, 35, v200
	v_cmp_lt_u32_e64 s[94:95], s91, v150
	v_cmp_lt_u32_e64 s[86:87], s91, v151
	v_cmp_lt_u32_e64 s[0:1], s91, v152
	v_cmp_lt_u32_e64 s[2:3], s91, v153
	v_cndmask_b32_e64 v8, v8, v230, s[94:95]
	v_cndmask_b32_e64 v9, v9, v230, s[86:87]
	v_cndmask_b32_e64 v10, v10, v230, s[0:1]
	v_cndmask_b32_e64 v11, v11, v230, s[2:3]
	v_sub_u32_e32 v150, 48, v200
	v_sub_u32_e32 v151, 49, v200
	v_sub_u32_e32 v152, 50, v200
	v_sub_u32_e32 v153, 51, v200
	v_cmp_lt_u32_e64 s[94:95], s91, v150
	v_cmp_lt_u32_e64 s[86:87], s91, v151
	v_cmp_lt_u32_e64 s[0:1], s91, v152
	v_cmp_lt_u32_e64 s[2:3], s91, v153
	v_cndmask_b32_e64 v12, v12, v230, s[94:95]
	v_cndmask_b32_e64 v13, v13, v230, s[86:87]
	v_cndmask_b32_e64 v14, v14, v230, s[0:1]
	v_cndmask_b32_e64 v15, v15, v230, s[2:3]
	v_sub_u32_e32 v150, 64, v200
	v_sub_u32_e32 v151, 0x41, v200
	v_sub_u32_e32 v152, 0x42, v200
	v_sub_u32_e32 v153, 0x43, v200
	v_cmp_lt_u32_e64 s[94:95], s91, v150
	v_cmp_lt_u32_e64 s[86:87], s91, v151
	v_cmp_lt_u32_e64 s[0:1], s91, v152
	v_cmp_lt_u32_e64 s[2:3], s91, v153
	v_cndmask_b32_e64 v16, v16, v230, s[94:95]
	v_cndmask_b32_e64 v17, v17, v230, s[86:87]
	v_cndmask_b32_e64 v18, v18, v230, s[0:1]
	v_cndmask_b32_e64 v19, v19, v230, s[2:3]
	v_sub_u32_e32 v150, 0x50, v200
	v_sub_u32_e32 v151, 0x51, v200
	v_sub_u32_e32 v152, 0x52, v200
	v_sub_u32_e32 v153, 0x53, v200
	v_cmp_lt_u32_e64 s[94:95], s91, v150
	v_cmp_lt_u32_e64 s[86:87], s91, v151
	v_cmp_lt_u32_e64 s[0:1], s91, v152
	v_cmp_lt_u32_e64 s[2:3], s91, v153
	v_cndmask_b32_e64 v20, v20, v230, s[94:95]
	v_cndmask_b32_e64 v21, v21, v230, s[86:87]
	v_cndmask_b32_e64 v22, v22, v230, s[0:1]
	v_cndmask_b32_e64 v23, v23, v230, s[2:3]
	v_sub_u32_e32 v150, 0x60, v200
	v_sub_u32_e32 v151, 0x61, v200
	v_sub_u32_e32 v152, 0x62, v200
	v_sub_u32_e32 v153, 0x63, v200
	v_cmp_lt_u32_e64 s[94:95], s91, v150
	v_cmp_lt_u32_e64 s[86:87], s91, v151
	v_cmp_lt_u32_e64 s[0:1], s91, v152
	v_cmp_lt_u32_e64 s[2:3], s91, v153
	v_cndmask_b32_e64 v24, v24, v230, s[94:95]
	v_cndmask_b32_e64 v25, v25, v230, s[86:87]
	v_cndmask_b32_e64 v26, v26, v230, s[0:1]
	v_cndmask_b32_e64 v27, v27, v230, s[2:3]
	v_sub_u32_e32 v150, 0x70, v200
	v_sub_u32_e32 v151, 0x71, v200
	v_sub_u32_e32 v152, 0x72, v200
	v_sub_u32_e32 v153, 0x73, v200
	v_cmp_lt_u32_e64 s[94:95], s91, v150
	v_cmp_lt_u32_e64 s[86:87], s91, v151
	v_cmp_lt_u32_e64 s[0:1], s91, v152
	v_cmp_lt_u32_e64 s[2:3], s91, v153
	v_cndmask_b32_e64 v28, v28, v230, s[94:95]
	v_cndmask_b32_e64 v29, v29, v230, s[86:87]
	v_cndmask_b32_e64 v30, v30, v230, s[0:1]
	v_cndmask_b32_e64 v31, v31, v230, s[2:3]
	v_sub_u32_e32 v150, 0x80, v200
	v_sub_u32_e32 v151, 0x81, v200
	v_sub_u32_e32 v152, 0x82, v200
	v_sub_u32_e32 v153, 0x83, v200
	v_cmp_lt_u32_e64 s[94:95], s91, v150
	v_cmp_lt_u32_e64 s[86:87], s91, v151
	v_cmp_lt_u32_e64 s[0:1], s91, v152
	v_cmp_lt_u32_e64 s[2:3], s91, v153
	v_cndmask_b32_e64 v32, v32, v230, s[94:95]
	v_cndmask_b32_e64 v33, v33, v230, s[86:87]
	v_cndmask_b32_e64 v34, v34, v230, s[0:1]
	v_cndmask_b32_e64 v35, v35, v230, s[2:3]

.Latt_noedge_2:
	s_nop 1
	v_max3_f32 v186, v36, v37, v38
	v_max3_f32 v186, v186, v39, v40
	v_max3_f32 v186, v186, v41, v42
	v_max3_f32 v186, v186, v43, v44
	v_max3_f32 v186, v186, v45, v46
	v_max3_f32 v186, v186, v47, v48
	v_max3_f32 v186, v186, v49, v50
	v_max3_f32 v186, v186, v51, v52
	v_max3_f32 v186, v186, v53, v54
	v_max3_f32 v186, v186, v55, v56
	v_max3_f32 v186, v186, v57, v58
	v_max3_f32 v186, v186, v59, v60
	v_max3_f32 v186, v186, v61, v62
	v_max3_f32 v186, v186, v63, v64
	v_max3_f32 v186, v186, v65, v66
	v_max3_f32 v186, v186, v67, v68
	v_max3_f32 v186, v186, v69, v70
	v_max_f32_e32 v186, v186, v71
	v_mov_b32_e32 v146, v186
	s_nop 1
	v_permlane16_swap_b32_e32 v186, v146
	v_max_f32_e32 v186, v186, v146
	v_mov_b32_e32 v146, v186
	s_nop 1
	v_permlane32_swap_b32_e32 v186, v146
	v_max_f32_e32 v186, v186, v146
	v_pk_add_f32 v[36:37], v[36:37], v[186:187] op_sel_hi:[1,0] neg_lo:[0,1] neg_hi:[0,1]
	v_pk_add_f32 v[38:39], v[38:39], v[186:187] op_sel_hi:[1,0] neg_lo:[0,1] neg_hi:[0,1]
	v_pk_add_f32 v[40:41], v[40:41], v[186:187] op_sel_hi:[1,0] neg_lo:[0,1] neg_hi:[0,1]
	v_pk_add_f32 v[42:43], v[42:43], v[186:187] op_sel_hi:[1,0] neg_lo:[0,1] neg_hi:[0,1]
	v_exp_f32_e32 v36, v36
	v_exp_f32_e32 v37, v37
	v_exp_f32_e32 v38, v38
	v_exp_f32_e32 v39, v39
	v_pk_add_f32 v[44:45], v[44:45], v[186:187] op_sel_hi:[1,0] neg_lo:[0,1] neg_hi:[0,1]
	v_pk_add_f32 v[46:47], v[46:47], v[186:187] op_sel_hi:[1,0] neg_lo:[0,1] neg_hi:[0,1]
	v_exp_f32_e32 v40, v40
	v_exp_f32_e32 v41, v41
	v_exp_f32_e32 v42, v42
	v_exp_f32_e32 v43, v43
	v_pk_add_f32 v[48:49], v[48:49], v[186:187] op_sel_hi:[1,0] neg_lo:[0,1] neg_hi:[0,1]
	v_pk_add_f32 v[50:51], v[50:51], v[186:187] op_sel_hi:[1,0] neg_lo:[0,1] neg_hi:[0,1]
	v_exp_f32_e32 v44, v44
	v_exp_f32_e32 v45, v45
	v_exp_f32_e32 v46, v46
	v_exp_f32_e32 v47, v47
	v_pk_add_f32 v[52:53], v[52:53], v[186:187] op_sel_hi:[1,0] neg_lo:[0,1] neg_hi:[0,1]
	v_pk_add_f32 v[54:55], v[54:55], v[186:187] op_sel_hi:[1,0] neg_lo:[0,1] neg_hi:[0,1]
	v_exp_f32_e32 v48, v48
	v_exp_f32_e32 v49, v49
	v_exp_f32_e32 v50, v50
	v_exp_f32_e32 v51, v51
	v_pk_add_f32 v[56:57], v[56:57], v[186:187] op_sel_hi:[1,0] neg_lo:[0,1] neg_hi:[0,1]
	v_pk_add_f32 v[58:59], v[58:59], v[186:187] op_sel_hi:[1,0] neg_lo:[0,1] neg_hi:[0,1]
	v_exp_f32_e32 v52, v52
	v_exp_f32_e32 v53, v53
	v_exp_f32_e32 v54, v54
	v_exp_f32_e32 v55, v55
	v_pk_add_f32 v[60:61], v[60:61], v[186:187] op_sel_hi:[1,0] neg_lo:[0,1] neg_hi:[0,1]
	v_pk_add_f32 v[62:63], v[62:63], v[186:187] op_sel_hi:[1,0] neg_lo:[0,1] neg_hi:[0,1]
	v_exp_f32_e32 v56, v56
	v_exp_f32_e32 v57, v57
	v_exp_f32_e32 v58, v58
	v_exp_f32_e32 v59, v59
	v_pk_add_f32 v[64:65], v[64:65], v[186:187] op_sel_hi:[1,0] neg_lo:[0,1] neg_hi:[0,1]
	v_pk_add_f32 v[66:67], v[66:67], v[186:187] op_sel_hi:[1,0] neg_lo:[0,1] neg_hi:[0,1]
	v_exp_f32_e32 v60, v60
	v_exp_f32_e32 v61, v61
	v_exp_f32_e32 v62, v62
	v_exp_f32_e32 v63, v63
	v_pk_add_f32 v[68:69], v[68:69], v[186:187] op_sel_hi:[1,0] neg_lo:[0,1] neg_hi:[0,1]
	v_pk_add_f32 v[70:71], v[70:71], v[186:187] op_sel_hi:[1,0] neg_lo:[0,1] neg_hi:[0,1]
	v_exp_f32_e32 v64, v64
	v_exp_f32_e32 v65, v65
	v_exp_f32_e32 v66, v66
	v_exp_f32_e32 v67, v67
	v_exp_f32_e32 v68, v68
	v_exp_f32_e32 v69, v69
	v_exp_f32_e32 v70, v70
	v_exp_f32_e32 v71, v71
	s_nop 0
	v_pk_add_f32 v[146:147], v[36:37], v[38:39]
	v_pk_add_f32 v[148:149], v[40:41], v[42:43]
	v_pk_add_f32 v[146:147], v[146:147], v[44:45]
	v_pk_add_f32 v[148:149], v[148:149], v[46:47]
	v_pk_add_f32 v[146:147], v[146:147], v[48:49]
	v_pk_add_f32 v[148:149], v[148:149], v[50:51]
	v_pk_add_f32 v[146:147], v[146:147], v[52:53]
	v_pk_add_f32 v[148:149], v[148:149], v[54:55]
	v_pk_add_f32 v[146:147], v[146:147], v[56:57]
	v_pk_add_f32 v[148:149], v[148:149], v[58:59]
	v_pk_add_f32 v[146:147], v[146:147], v[60:61]
	v_pk_add_f32 v[148:149], v[148:149], v[62:63]
	v_pk_add_f32 v[146:147], v[146:147], v[64:65]
	v_pk_add_f32 v[148:149], v[148:149], v[66:67]
	v_pk_add_f32 v[146:147], v[146:147], v[68:69]
	v_pk_add_f32 v[148:149], v[148:149], v[70:71]
	s_nop 0
	v_pk_add_f32 v[146:147], v[146:147], v[148:149]
	s_nop 0
	v_add_f32_e32 v187, v146, v147
	v_cvt_pk_bf16_f32 v36, v36, v37
	v_cvt_pk_bf16_f32 v37, v38, v39
	v_cvt_pk_bf16_f32 v40, v40, v41
	v_cvt_pk_bf16_f32 v41, v42, v43
	v_cvt_pk_bf16_f32 v44, v44, v45
	v_cvt_pk_bf16_f32 v45, v46, v47
	v_cvt_pk_bf16_f32 v48, v48, v49
	v_cvt_pk_bf16_f32 v49, v50, v51
	v_cvt_pk_bf16_f32 v52, v52, v53
	v_cvt_pk_bf16_f32 v53, v54, v55
	v_cvt_pk_bf16_f32 v56, v56, v57
	v_cvt_pk_bf16_f32 v57, v58, v59
	v_cvt_pk_bf16_f32 v60, v60, v61
	v_cvt_pk_bf16_f32 v61, v62, v63
	v_cvt_pk_bf16_f32 v64, v64, v65
	v_cvt_pk_bf16_f32 v65, v66, v67
	v_cvt_pk_bf16_f32 v68, v68, v69
	v_cvt_pk_bf16_f32 v69, v70, v71
	v_mov_b32_e32 v146, v187
	s_nop 1
	v_permlane16_swap_b32_e32 v187, v146
	v_add_f32_e32 v187, v187, v146
	v_mov_b32_e32 v146, v187
	s_nop 1
	v_permlane32_swap_b32_e32 v187, v146
	v_add_f32_e32 v187, v187, v146
	s_waitcnt lgkmcnt(0)
	s_add_i32 s93, s76, 16
	s_mov_b32 m0, s14
	v_add_u32_e32 v164, s93, v231
	v_med3_i32 v164, v164, 0, s40
	v_lshl_or_b32 v164, v164, 7, v222
	global_load_lds_dwordx4 v164, s[24:25]
	s_add_i32 m0, s14, 0x400
	v_add_u32_e32 v165, s93, v232
	v_med3_i32 v165, v165, 0, s40
	v_lshl_or_b32 v165, v165, 7, v222
	global_load_lds_dwordx4 v165, s[24:25]
	s_waitcnt vmcnt(8)
	v_add_u32_e32 v154, s15, v225
	v_add_u32_e32 v155, s15, v226
	v_add_u32_e32 v156, s15, v227
	v_add_u32_e32 v157, s15, v228
	ds_read_b64_tr_b16 v[202:203], v154
	ds_read_b64_tr_b16 v[204:205], v155
	ds_read_b64_tr_b16 v[206:207], v156
	ds_read_b64_tr_b16 v[208:209], v157
	v_mfma_f32_16x16x16_bf16 v[96:99], v[88:89], v[0:1], 0
	v_mfma_f32_16x16x16_bf16 v[100:103], v[90:91], v[0:1], 0
	v_mfma_f32_16x16x16_bf16 v[104:107], v[92:93], v[0:1], 0
	v_mfma_f32_16x16x16_bf16 v[108:111], v[94:95], v[0:1], 0
	s_waitcnt lgkmcnt(0)
	s_add_i32 s93, s76, 32
	s_mov_b32 m0, s15
	v_add_u32_e32 v164, s93, v231
	v_med3_i32 v164, v164, 0, s40
	v_lshl_or_b32 v164, v164, 7, v222
	global_load_lds_dwordx4 v164, s[24:25]
	s_add_i32 m0, s15, 0x400
	v_add_u32_e32 v165, s93, v232
	v_med3_i32 v165, v165, 0, s40
	v_lshl_or_b32 v165, v165, 7, v222
	global_load_lds_dwordx4 v165, s[24:25]
	s_waitcnt vmcnt(8)
	v_add_u32_e32 v154, s16, v225
	v_add_u32_e32 v155, s16, v226
	v_add_u32_e32 v156, s16, v227
	v_add_u32_e32 v157, s16, v228
	ds_read_b64_tr_b16 v[88:89], v154
	ds_read_b64_tr_b16 v[90:91], v155
	ds_read_b64_tr_b16 v[92:93], v156
	ds_read_b64_tr_b16 v[94:95], v157
	v_mfma_f32_16x16x16_bf16 v[96:99], v[202:203], v[4:5], v[96:99]
	v_mfma_f32_16x16x16_bf16 v[112:115], v[202:203], v[36:37], 0
	v_mfma_f32_16x16x16_bf16 v[100:103], v[204:205], v[4:5], v[100:103]
	v_mfma_f32_16x16x16_bf16 v[116:119], v[204:205], v[36:37], 0
	v_mfma_f32_16x16x16_bf16 v[104:107], v[206:207], v[4:5], v[104:107]
	v_mfma_f32_16x16x16_bf16 v[120:123], v[206:207], v[36:37], 0
	v_mfma_f32_16x16x16_bf16 v[108:111], v[208:209], v[4:5], v[108:111]
	v_mfma_f32_16x16x16_bf16 v[124:127], v[208:209], v[36:37], 0
	s_waitcnt lgkmcnt(0)
	s_add_i32 s93, s76, 48
	s_mov_b32 m0, s16
	v_add_u32_e32 v164, s93, v231
	v_med3_i32 v164, v164, 0, s40
	v_lshl_or_b32 v164, v164, 7, v222
	global_load_lds_dwordx4 v164, s[24:25]
	s_add_i32 m0, s16, 0x400
	v_add_u32_e32 v165, s93, v232
	v_med3_i32 v165, v165, 0, s40
	v_lshl_or_b32 v165, v165, 7, v222
	global_load_lds_dwordx4 v165, s[24:25]
	s_waitcnt vmcnt(8)
	v_add_u32_e32 v154, s12, v225
	v_add_u32_e32 v155, s12, v226
	v_add_u32_e32 v156, s12, v227
	v_add_u32_e32 v157, s12, v228
	ds_read_b64_tr_b16 v[202:203], v154
	ds_read_b64_tr_b16 v[204:205], v155
	ds_read_b64_tr_b16 v[206:207], v156
	ds_read_b64_tr_b16 v[208:209], v157
	v_mfma_f32_16x16x16_bf16 v[96:99], v[88:89], v[8:9], v[96:99]
	v_mfma_f32_16x16x16_bf16 v[112:115], v[88:89], v[40:41], v[112:115]
	v_mfma_f32_16x16x16_bf16 v[100:103], v[90:91], v[8:9], v[100:103]
	v_mfma_f32_16x16x16_bf16 v[116:119], v[90:91], v[40:41], v[116:119]
	v_mfma_f32_16x16x16_bf16 v[104:107], v[92:93], v[8:9], v[104:107]
	v_mfma_f32_16x16x16_bf16 v[120:123], v[92:93], v[40:41], v[120:123]
	v_mfma_f32_16x16x16_bf16 v[108:111], v[94:95], v[8:9], v[108:111]
	v_mfma_f32_16x16x16_bf16 v[124:127], v[94:95], v[40:41], v[124:127]
	s_waitcnt lgkmcnt(0)
	s_add_i32 s93, s76, 64
	s_mov_b32 m0, s12
	v_add_u32_e32 v164, s93, v231
	v_med3_i32 v164, v164, 0, s40
	v_lshl_or_b32 v164, v164, 7, v222
	global_load_lds_dwordx4 v164, s[24:25]
	s_add_i32 m0, s12, 0x400
	v_add_u32_e32 v165, s93, v232
	v_med3_i32 v165, v165, 0, s40
	v_lshl_or_b32 v165, v165, 7, v222
	global_load_lds_dwordx4 v165, s[24:25]
	s_waitcnt vmcnt(8)
	v_add_u32_e32 v154, s13, v225
	v_add_u32_e32 v155, s13, v226
	v_add_u32_e32 v156, s13, v227
	v_add_u32_e32 v157, s13, v228
	ds_read_b64_tr_b16 v[88:89], v154
	ds_read_b64_tr_b16 v[90:91], v155
	ds_read_b64_tr_b16 v[92:93], v156
	ds_read_b64_tr_b16 v[94:95], v157
	v_mfma_f32_16x16x16_bf16 v[96:99], v[202:203], v[12:13], v[96:99]
	v_mfma_f32_16x16x16_bf16 v[112:115], v[202:203], v[44:45], v[112:115]
	v_mfma_f32_16x16x16_bf16 v[100:103], v[204:205], v[12:13], v[100:103]
	v_mfma_f32_16x16x16_bf16 v[116:119], v[204:205], v[44:45], v[116:119]
	v_mfma_f32_16x16x16_bf16 v[104:107], v[206:207], v[12:13], v[104:107]
	v_mfma_f32_16x16x16_bf16 v[120:123], v[206:207], v[44:45], v[120:123]
	v_mfma_f32_16x16x16_bf16 v[108:111], v[208:209], v[12:13], v[108:111]
	v_mfma_f32_16x16x16_bf16 v[124:127], v[208:209], v[44:45], v[124:127]
	s_waitcnt lgkmcnt(0)
	s_add_i32 s93, s76, 0x50
	s_mov_b32 m0, s13
	v_add_u32_e32 v164, s93, v231
	v_med3_i32 v164, v164, 0, s40
	v_lshl_or_b32 v164, v164, 7, v222
	global_load_lds_dwordx4 v164, s[24:25]
	s_add_i32 m0, s13, 0x400
	v_add_u32_e32 v165, s93, v232
	v_med3_i32 v165, v165, 0, s40
	v_lshl_or_b32 v165, v165, 7, v222
	global_load_lds_dwordx4 v165, s[24:25]
	s_waitcnt vmcnt(8)
	v_add_u32_e32 v154, s14, v225
	v_add_u32_e32 v155, s14, v226
	v_add_u32_e32 v156, s14, v227
	v_add_u32_e32 v157, s14, v228
	ds_read_b64_tr_b16 v[202:203], v154
	ds_read_b64_tr_b16 v[204:205], v155
	ds_read_b64_tr_b16 v[206:207], v156
	ds_read_b64_tr_b16 v[208:209], v157
	v_mfma_f32_16x16x16_bf16 v[96:99], v[88:89], v[16:17], v[96:99]
	v_mfma_f32_16x16x16_bf16 v[112:115], v[88:89], v[48:49], v[112:115]
	v_mfma_f32_16x16x16_bf16 v[100:103], v[90:91], v[16:17], v[100:103]
	v_mfma_f32_16x16x16_bf16 v[116:119], v[90:91], v[48:49], v[116:119]
	v_mfma_f32_16x16x16_bf16 v[104:107], v[92:93], v[16:17], v[104:107]
	v_mfma_f32_16x16x16_bf16 v[120:123], v[92:93], v[48:49], v[120:123]
	v_mfma_f32_16x16x16_bf16 v[108:111], v[94:95], v[16:17], v[108:111]
	v_mfma_f32_16x16x16_bf16 v[124:127], v[94:95], v[48:49], v[124:127]
	s_waitcnt lgkmcnt(0)
	s_add_i32 s93, s79, 0
	s_mov_b32 m0, s14
	v_add_u32_e32 v164, s93, v162
	v_lshl_or_b32 v164, v164, 7, v220
	global_load_lds_dwordx4 v164, s[18:19]
	s_add_i32 m0, s14, 0x400
	v_add_u32_e32 v165, s93, v163
	v_lshl_or_b32 v165, v165, 7, v221
	global_load_lds_dwordx4 v165, s[18:19]
	s_waitcnt vmcnt(8)
	v_add_u32_e32 v154, s15, v225
	v_add_u32_e32 v155, s15, v226
	v_add_u32_e32 v156, s15, v227
	v_add_u32_e32 v157, s15, v228
	ds_read_b64_tr_b16 v[88:89], v154
	ds_read_b64_tr_b16 v[90:91], v155
	ds_read_b64_tr_b16 v[92:93], v156
	ds_read_b64_tr_b16 v[94:95], v157
	v_mfma_f32_16x16x16_bf16 v[96:99], v[202:203], v[20:21], v[96:99]
	v_mfma_f32_16x16x16_bf16 v[112:115], v[202:203], v[52:53], v[112:115]
	v_mfma_f32_16x16x16_bf16 v[100:103], v[204:205], v[20:21], v[100:103]
	v_mfma_f32_16x16x16_bf16 v[116:119], v[204:205], v[52:53], v[116:119]
	v_mfma_f32_16x16x16_bf16 v[104:107], v[206:207], v[20:21], v[104:107]
	v_mfma_f32_16x16x16_bf16 v[120:123], v[206:207], v[52:53], v[120:123]
	v_mfma_f32_16x16x16_bf16 v[108:111], v[208:209], v[20:21], v[108:111]
	v_mfma_f32_16x16x16_bf16 v[124:127], v[208:209], v[52:53], v[124:127]
	s_waitcnt lgkmcnt(0)
	s_add_i32 s93, s79, 64
	s_mov_b32 m0, s15
	v_add_u32_e32 v164, s93, v162
	v_lshl_or_b32 v164, v164, 7, v220
	global_load_lds_dwordx4 v164, s[18:19]
	s_add_i32 m0, s15, 0x400
	v_add_u32_e32 v165, s93, v163
	v_lshl_or_b32 v165, v165, 7, v221
	global_load_lds_dwordx4 v165, s[18:19]
	s_waitcnt vmcnt(8)
	v_add_u32_e32 v154, s16, v225
	v_add_u32_e32 v155, s16, v226
	v_add_u32_e32 v156, s16, v227
	v_add_u32_e32 v157, s16, v228
	ds_read_b64_tr_b16 v[202:203], v154
	ds_read_b64_tr_b16 v[204:205], v155
	ds_read_b64_tr_b16 v[206:207], v156
	ds_read_b64_tr_b16 v[208:209], v157
	v_mfma_f32_16x16x16_bf16 v[96:99], v[88:89], v[24:25], v[96:99]
	v_mfma_f32_16x16x16_bf16 v[112:115], v[88:89], v[56:57], v[112:115]
	v_mfma_f32_16x16x16_bf16 v[100:103], v[90:91], v[24:25], v[100:103]
	v_mfma_f32_16x16x16_bf16 v[116:119], v[90:91], v[56:57], v[116:119]
	v_mfma_f32_16x16x16_bf16 v[104:107], v[92:93], v[24:25], v[104:107]
	v_mfma_f32_16x16x16_bf16 v[120:123], v[92:93], v[56:57], v[120:123]
	v_mfma_f32_16x16x16_bf16 v[108:111], v[94:95], v[24:25], v[108:111]
	v_mfma_f32_16x16x16_bf16 v[124:127], v[94:95], v[56:57], v[124:127]
	s_waitcnt lgkmcnt(0)
	s_add_i32 s93, s79, 0xffffff00
	s_mov_b32 m0, s16
	v_add_u32_e32 v164, s93, v162
	v_med3_i32 v164, v164, 0, s40
	v_lshl_or_b32 v164, v164, 7, v220
	global_load_lds_dwordx4 v164, s[20:21]
	s_add_i32 m0, s16, 0x400
	v_add_u32_e32 v165, s93, v163
	v_med3_i32 v165, v165, 0, s40
	v_lshl_or_b32 v165, v165, 7, v221
	global_load_lds_dwordx4 v165, s[20:21]
	s_waitcnt vmcnt(8)
	v_add_u32_e32 v154, s12, v225
	v_add_u32_e32 v155, s12, v226
	v_add_u32_e32 v156, s12, v227
	v_add_u32_e32 v157, s12, v228
	ds_read_b64_tr_b16 v[88:89], v154
	ds_read_b64_tr_b16 v[90:91], v155
	ds_read_b64_tr_b16 v[92:93], v156
	ds_read_b64_tr_b16 v[94:95], v157
	v_mfma_f32_16x16x16_bf16 v[96:99], v[202:203], v[28:29], v[96:99]
	v_mfma_f32_16x16x16_bf16 v[112:115], v[202:203], v[60:61], v[112:115]
	v_mfma_f32_16x16x16_bf16 v[100:103], v[204:205], v[28:29], v[100:103]
	v_mfma_f32_16x16x16_bf16 v[116:119], v[204:205], v[60:61], v[116:119]
	v_mfma_f32_16x16x16_bf16 v[104:107], v[206:207], v[28:29], v[104:107]
	v_mfma_f32_16x16x16_bf16 v[120:123], v[206:207], v[60:61], v[120:123]
	v_mfma_f32_16x16x16_bf16 v[108:111], v[208:209], v[28:29], v[108:111]
	v_mfma_f32_16x16x16_bf16 v[124:127], v[208:209], v[60:61], v[124:127]
	s_waitcnt lgkmcnt(0)
	s_add_i32 s93, s79, 0xffffff40
	s_mov_b32 m0, s12
	v_add_u32_e32 v164, s93, v162
	v_med3_i32 v164, v164, 0, s40
	v_lshl_or_b32 v164, v164, 7, v220
	global_load_lds_dwordx4 v164, s[20:21]
	s_add_i32 m0, s12, 0x400
	v_add_u32_e32 v165, s93, v163
	v_med3_i32 v165, v165, 0, s40
	v_lshl_or_b32 v165, v165, 7, v221
	global_load_lds_dwordx4 v165, s[20:21]
	s_waitcnt vmcnt(8)
	v_add_u32_e32 v154, s13, v225
	v_add_u32_e32 v155, s13, v226
	v_add_u32_e32 v156, s13, v227
	v_add_u32_e32 v157, s13, v228
	ds_read_b64_tr_b16 v[202:203], v154
	ds_read_b64_tr_b16 v[204:205], v155
	ds_read_b64_tr_b16 v[206:207], v156
	ds_read_b64_tr_b16 v[208:209], v157
	v_mfma_f32_16x16x16_bf16 v[96:99], v[88:89], v[32:33], v[96:99]
	v_mfma_f32_16x16x16_bf16 v[112:115], v[88:89], v[64:65], v[112:115]
	v_mfma_f32_16x16x16_bf16 v[100:103], v[90:91], v[32:33], v[100:103]
	v_mfma_f32_16x16x16_bf16 v[116:119], v[90:91], v[64:65], v[116:119]
	v_mfma_f32_16x16x16_bf16 v[104:107], v[92:93], v[32:33], v[104:107]
	v_mfma_f32_16x16x16_bf16 v[120:123], v[92:93], v[64:65], v[120:123]
	v_mfma_f32_16x16x16_bf16 v[108:111], v[94:95], v[32:33], v[108:111]
	v_mfma_f32_16x16x16_bf16 v[124:127], v[94:95], v[64:65], v[124:127]
	s_waitcnt lgkmcnt(0)
	s_add_i32 s93, s79, 0xffffff80
	s_mov_b32 m0, s13
	v_add_u32_e32 v164, s93, v162
	v_med3_i32 v164, v164, 0, s40
	v_lshl_or_b32 v164, v164, 7, v220
	global_load_lds_dwordx4 v164, s[20:21]
	s_add_i32 m0, s13, 0x400
	v_add_u32_e32 v165, s93, v163
	v_med3_i32 v165, v165, 0, s40
	v_lshl_or_b32 v165, v165, 7, v221
	global_load_lds_dwordx4 v165, s[20:21]
	v_mfma_f32_16x16x16_bf16 v[112:115], v[202:203], v[68:69], v[112:115]
	v_mfma_f32_16x16x16_bf16 v[116:119], v[204:205], v[68:69], v[116:119]
	v_mfma_f32_16x16x16_bf16 v[120:123], v[206:207], v[68:69], v[120:123]
	v_mfma_f32_16x16x16_bf16 v[124:127], v[208:209], v[68:69], v[124:127]
	s_and_saveexec_b64 s[80:81], s[74:75]
	ds_write_b64 v194, v[184:185]
	s_mov_b64 exec, s[80:81]
	ds_write_b128 v190, v[96:99]
	ds_write_b128 v191, v[100:103]
	ds_write_b128 v192, v[104:107]
	ds_write_b128 v193, v[108:111]
	s_and_saveexec_b64 s[80:81], s[74:75]
	ds_write_b64 v199, v[186:187]
	s_mov_b64 exec, s[80:81]
	ds_write_b128 v195, v[112:115]
	ds_write_b128 v196, v[116:119]
	ds_write_b128 v197, v[120:123]
	ds_write_b128 v198, v[124:127]
	s_waitcnt lgkmcnt(0)
	s_barrier
	s_add_i32 s76, s38, s83
	s_add_i32 s79, s38, s84
	v_lshlrev_b32_e32 v231, 2, v218
	v_add_u32_e32 v232, 8, v218
	v_lshlrev_b32_e32 v232, 2, v232
	v_lshlrev_b32_e32 v162, 4, v218
	v_add_u32_e32 v163, 8, v218
	v_lshlrev_b32_e32 v163, 4, v163
	s_waitcnt vmcnt(8)
	v_add_u32_e32 v154, s14, v223
	v_add_u32_e32 v155, s14, v224
	ds_read_b128 v[72:75], v154
	ds_read_b128 v[76:79], v155
	s_waitcnt lgkmcnt(0)
	s_add_i32 s93, s76, 0xffffffc0
	s_mov_b32 m0, s14
	v_add_u32_e32 v164, s93, v231
	v_med3_i32 v164, v164, 0, s40
	v_lshl_or_b32 v164, v164, 7, v220
	global_load_lds_dwordx4 v164, s[20:21]
	s_add_i32 m0, s14, 0x400
	v_add_u32_e32 v165, s93, v232
	v_med3_i32 v165, v165, 0, s40
	v_lshl_or_b32 v165, v165, 7, v221
	global_load_lds_dwordx4 v165, s[20:21]
	s_waitcnt vmcnt(8)
	v_add_u32_e32 v154, s15, v223
	v_add_u32_e32 v155, s15, v224
	ds_read_b128 v[80:83], v154
	ds_read_b128 v[84:87], v155
	s_waitcnt lgkmcnt(0)
	s_add_i32 s93, s76, 0
	s_mov_b32 m0, s15
	v_add_u32_e32 v164, s93, v231
	v_med3_i32 v164, v164, 0, s40
	v_lshl_or_b32 v164, v164, 7, v220
	global_load_lds_dwordx4 v164, s[20:21]
	s_add_i32 m0, s15, 0x400
	v_add_u32_e32 v165, s93, v232
	v_med3_i32 v165, v165, 0, s40
	v_lshl_or_b32 v165, v165, 7, v221
	global_load_lds_dwordx4 v165, s[20:21]
	s_waitcnt vmcnt(8)
	v_add_u32_e32 v154, s16, v223
	v_add_u32_e32 v155, s16, v224
	ds_read_b128 v[88:91], v154
	ds_read_b128 v[92:95], v155
	s_waitcnt lgkmcnt(0)
	s_add_i32 s93, s76, 64
	s_mov_b32 m0, s16
	v_add_u32_e32 v164, s93, v231
	v_med3_i32 v164, v164, 0, s40
	v_lshl_or_b32 v164, v164, 7, v220
	global_load_lds_dwordx4 v164, s[20:21]
	s_add_i32 m0, s16, 0x400
	v_add_u32_e32 v165, s93, v232
	v_med3_i32 v165, v165, 0, s40
	v_lshl_or_b32 v165, v165, 7, v221
	global_load_lds_dwordx4 v165, s[20:21]
	s_waitcnt vmcnt(8)
	v_add_u32_e32 v154, s12, v223
	v_add_u32_e32 v155, s12, v224
	ds_read_b128 v[202:205], v154
	ds_read_b128 v[206:209], v155
	v_mfma_f32_16x16x32_bf16 v[0:3], v[88:91], v[72:75], 0
	v_mfma_f32_16x16x32_bf16 v[0:3], v[92:95], v[76:79], v[0:3]
	s_waitcnt lgkmcnt(0)
	s_add_i32 s93, s76, 0x80
	s_mov_b32 m0, s12
	v_add_u32_e32 v164, s93, v231
	v_med3_i32 v164, v164, 0, s40
	v_lshl_or_b32 v164, v164, 7, v220
	global_load_lds_dwordx4 v164, s[20:21]
	s_add_i32 m0, s12, 0x400
	v_add_u32_e32 v165, s93, v232
	v_med3_i32 v165, v165, 0, s40
	v_lshl_or_b32 v165, v165, 7, v221
	global_load_lds_dwordx4 v165, s[20:21]
	s_waitcnt vmcnt(8)
	v_add_u32_e32 v154, s13, v223
	v_add_u32_e32 v155, s13, v224
	ds_read_b128 v[88:91], v154
	ds_read_b128 v[92:95], v155
	v_mfma_f32_16x16x32_bf16 v[4:7], v[202:205], v[72:75], 0
	v_mfma_f32_16x16x32_bf16 v[36:39], v[202:205], v[80:83], 0
	v_mfma_f32_16x16x32_bf16 v[4:7], v[206:209], v[76:79], v[4:7]
	v_mfma_f32_16x16x32_bf16 v[36:39], v[206:209], v[84:87], v[36:39]
	s_waitcnt lgkmcnt(0)
	s_add_i32 s93, s76, 0xc0
	s_mov_b32 m0, s13
	v_add_u32_e32 v164, s93, v231
	v_med3_i32 v164, v164, 0, s40
	v_lshl_or_b32 v164, v164, 7, v220
	global_load_lds_dwordx4 v164, s[20:21]
	s_add_i32 m0, s13, 0x400
	v_add_u32_e32 v165, s93, v232
	v_med3_i32 v165, v165, 0, s40
	v_lshl_or_b32 v165, v165, 7, v221
	global_load_lds_dwordx4 v165, s[20:21]
	s_waitcnt vmcnt(8)
	v_add_u32_e32 v154, s14, v223
	v_add_u32_e32 v155, s14, v224
	ds_read_b128 v[202:205], v154
	ds_read_b128 v[206:209], v155
	v_mfma_f32_16x16x32_bf16 v[8:11], v[88:91], v[72:75], 0
	v_mfma_f32_16x16x32_bf16 v[40:43], v[88:91], v[80:83], 0
	v_mfma_f32_16x16x32_bf16 v[8:11], v[92:95], v[76:79], v[8:11]
	v_mfma_f32_16x16x32_bf16 v[40:43], v[92:95], v[84:87], v[40:43]
	v_mov_b32_e32 v188, s83
	v_lshl_add_u32 v188, v216, 2, v188
	v_lshrrev_b32_e32 v146, 4, v188
	v_xor_b32_e32 v146, v146, v188
	v_and_b32_e32 v146, 15, v146
	v_lshlrev_b32_e32 v147, 8, v188
	v_or_b32_e32 v148, 0, v217
	s_waitcnt lgkmcnt(0)
	s_add_i32 s93, s76, 0x100
	s_mov_b32 m0, s14
	v_add_u32_e32 v164, s93, v231
	v_med3_i32 v164, v164, 0, s40
	v_lshl_or_b32 v164, v164, 7, v220
	global_load_lds_dwordx4 v164, s[20:21]
	s_add_i32 m0, s14, 0x400
	v_add_u32_e32 v165, s93, v232
	v_med3_i32 v165, v165, 0, s40
	v_lshl_or_b32 v165, v165, 7, v221
	global_load_lds_dwordx4 v165, s[20:21]
	s_waitcnt vmcnt(8)
	v_add_u32_e32 v154, s15, v223
	v_add_u32_e32 v155, s15, v224
	ds_read_b128 v[88:91], v154
	ds_read_b128 v[92:95], v155
	v_mfma_f32_16x16x32_bf16 v[12:15], v[202:205], v[72:75], 0
	v_mfma_f32_16x16x32_bf16 v[44:47], v[202:205], v[80:83], 0
	v_mfma_f32_16x16x32_bf16 v[12:15], v[206:209], v[76:79], v[12:15]
	v_mfma_f32_16x16x32_bf16 v[44:47], v[206:209], v[84:87], v[44:47]
	v_xor_b32_e32 v148, v148, v146
	v_lshl_add_u32 v190, v148, 4, v147
	v_or_b32_e32 v148, 4, v217
	v_xor_b32_e32 v148, v148, v146
	v_lshl_add_u32 v191, v148, 4, v147
	v_or_b32_e32 v148, 8, v217
	v_xor_b32_e32 v148, v148, v146
	s_waitcnt lgkmcnt(0)
	s_add_i32 s93, s76, 0x140
	s_mov_b32 m0, s15
	v_add_u32_e32 v164, s93, v231
	v_med3_i32 v164, v164, 0, s40
	v_lshl_or_b32 v164, v164, 7, v220
	global_load_lds_dwordx4 v164, s[20:21]
	s_add_i32 m0, s15, 0x400
	v_add_u32_e32 v165, s93, v232
	v_med3_i32 v165, v165, 0, s40
	v_lshl_or_b32 v165, v165, 7, v221
	global_load_lds_dwordx4 v165, s[20:21]
	s_waitcnt vmcnt(8)
	v_add_u32_e32 v154, s16, v223
	v_add_u32_e32 v155, s16, v224
	ds_read_b128 v[202:205], v154
	ds_read_b128 v[206:209], v155
	v_mfma_f32_16x16x32_bf16 v[16:19], v[88:91], v[72:75], 0
	v_mfma_f32_16x16x32_bf16 v[48:51], v[88:91], v[80:83], 0
	v_mfma_f32_16x16x32_bf16 v[16:19], v[92:95], v[76:79], v[16:19]
	v_mfma_f32_16x16x32_bf16 v[48:51], v[92:95], v[84:87], v[48:51]
	v_lshl_add_u32 v192, v148, 4, v147
	v_or_b32_e32 v148, 12, v217
	v_xor_b32_e32 v148, v148, v146
	v_lshl_add_u32 v193, v148, 4, v147
	v_lshlrev_b32_e32 v194, 3, v188
	v_add_u32_e32 v194, 0x10000, v194
	ds_read_b64 v[144:145], v194
	s_waitcnt lgkmcnt(0)
	s_add_i32 s93, s76, 0xffffff00
	s_mov_b32 m0, s16
	v_add_u32_e32 v164, s93, v231
	v_med3_i32 v164, v164, 0, s40
	v_lshl_or_b32 v164, v164, 7, v222
	global_load_lds_dwordx4 v164, s[24:25]
	s_add_i32 m0, s16, 0x400
	v_add_u32_e32 v165, s93, v232
	v_med3_i32 v165, v165, 0, s40
	v_lshl_or_b32 v165, v165, 7, v222
	global_load_lds_dwordx4 v165, s[24:25]
	s_waitcnt vmcnt(8)
	v_add_u32_e32 v154, s12, v223
	v_add_u32_e32 v155, s12, v224
	ds_read_b128 v[88:91], v154
	ds_read_b128 v[92:95], v155
	v_mfma_f32_16x16x32_bf16 v[20:23], v[202:205], v[72:75], 0
	v_mfma_f32_16x16x32_bf16 v[52:55], v[202:205], v[80:83], 0
	v_mfma_f32_16x16x32_bf16 v[20:23], v[206:209], v[76:79], v[20:23]
	v_mfma_f32_16x16x32_bf16 v[52:55], v[206:209], v[84:87], v[52:55]
	ds_read_b128 v[128:131], v190
	ds_read_b128 v[132:135], v191
	ds_read_b128 v[136:139], v192
	ds_read_b128 v[140:143], v193
	v_mov_b32_e32 v189, s83
	v_lshl_add_u32 v189, v216, 2, v189
	v_add_u32_e32 v189, 64, v189
	s_waitcnt lgkmcnt(0)
	s_add_i32 s93, s76, 0xffffff40
	s_mov_b32 m0, s12
	v_add_u32_e32 v164, s93, v231
	v_med3_i32 v164, v164, 0, s40
	v_lshl_or_b32 v164, v164, 7, v222
	global_load_lds_dwordx4 v164, s[24:25]
	s_add_i32 m0, s12, 0x400
	v_add_u32_e32 v165, s93, v232
	v_med3_i32 v165, v165, 0, s40
	v_lshl_or_b32 v165, v165, 7, v222
	global_load_lds_dwordx4 v165, s[24:25]
	s_waitcnt vmcnt(8)
	v_add_u32_e32 v154, s13, v223
	v_add_u32_e32 v155, s13, v224
	ds_read_b128 v[202:205], v154
	ds_read_b128 v[206:209], v155
	v_mfma_f32_16x16x32_bf16 v[24:27], v[88:91], v[72:75], 0
	v_mfma_f32_16x16x32_bf16 v[56:59], v[88:91], v[80:83], 0
	v_mfma_f32_16x16x32_bf16 v[24:27], v[92:95], v[76:79], v[24:27]
	v_mfma_f32_16x16x32_bf16 v[56:59], v[92:95], v[84:87], v[56:59]
	v_lshrrev_b32_e32 v146, 4, v189
	v_xor_b32_e32 v146, v146, v189
	v_and_b32_e32 v146, 15, v146
	v_lshlrev_b32_e32 v147, 8, v189
	v_or_b32_e32 v148, 0, v217
	v_xor_b32_e32 v148, v148, v146
	v_lshl_add_u32 v195, v148, 4, v147
	s_waitcnt lgkmcnt(0)
	s_add_i32 s93, s76, 0xffffff80
	s_mov_b32 m0, s13
	v_add_u32_e32 v164, s93, v231
	v_med3_i32 v164, v164, 0, s40
	v_lshl_or_b32 v164, v164, 7, v222
	global_load_lds_dwordx4 v164, s[24:25]
	s_add_i32 m0, s13, 0x400
	v_add_u32_e32 v165, s93, v232
	v_med3_i32 v165, v165, 0, s40
	v_lshl_or_b32 v165, v165, 7, v222
	global_load_lds_dwordx4 v165, s[24:25]
	s_waitcnt vmcnt(8)
	v_add_u32_e32 v154, s14, v223
	v_add_u32_e32 v155, s14, v224
	ds_read_b128 v[88:91], v154
	ds_read_b128 v[92:95], v155
	v_mfma_f32_16x16x32_bf16 v[28:31], v[202:205], v[72:75], 0
	v_mfma_f32_16x16x32_bf16 v[60:63], v[202:205], v[80:83], 0
	v_mfma_f32_16x16x32_bf16 v[28:31], v[206:209], v[76:79], v[28:31]
	v_mfma_f32_16x16x32_bf16 v[60:63], v[206:209], v[84:87], v[60:63]
	v_or_b32_e32 v148, 4, v217
	v_xor_b32_e32 v148, v148, v146
	v_lshl_add_u32 v196, v148, 4, v147
	v_or_b32_e32 v148, 8, v217
	v_xor_b32_e32 v148, v148, v146
	v_lshl_add_u32 v197, v148, 4, v147
	v_or_b32_e32 v148, 12, v217
	s_waitcnt lgkmcnt(0)
	s_add_i32 s93, s76, 0xffffffc0
	s_mov_b32 m0, s14
	v_add_u32_e32 v164, s93, v231
	v_med3_i32 v164, v164, 0, s40
	v_lshl_or_b32 v164, v164, 7, v222
	global_load_lds_dwordx4 v164, s[24:25]
	s_add_i32 m0, s14, 0x400
	v_add_u32_e32 v165, s93, v232
	v_med3_i32 v165, v165, 0, s40
	v_lshl_or_b32 v165, v165, 7, v222
	global_load_lds_dwordx4 v165, s[24:25]
	s_waitcnt vmcnt(8)
	v_add_u32_e32 v154, s15, v223
	v_add_u32_e32 v155, s15, v224
	ds_read_b128 v[202:205], v154
	ds_read_b128 v[206:209], v155
	v_mfma_f32_16x16x32_bf16 v[32:35], v[88:91], v[72:75], 0
	v_mfma_f32_16x16x32_bf16 v[64:67], v[88:91], v[80:83], 0
	v_mfma_f32_16x16x32_bf16 v[32:35], v[92:95], v[76:79], v[32:35]
	v_mfma_f32_16x16x32_bf16 v[64:67], v[92:95], v[84:87], v[64:67]
	v_xor_b32_e32 v148, v148, v146
	v_lshl_add_u32 v198, v148, 4, v147
	v_lshlrev_b32_e32 v199, 3, v189
	v_add_u32_e32 v199, 0x10000, v199
	ds_read_b64 v[182:183], v199
	ds_read_b128 v[166:169], v195
	ds_read_b128 v[170:173], v196
	s_waitcnt lgkmcnt(0)
	s_add_i32 s93, s76, 0
	s_mov_b32 m0, s15
	v_add_u32_e32 v164, s93, v231
	v_med3_i32 v164, v164, 0, s40
	v_lshl_or_b32 v164, v164, 7, v222
	global_load_lds_dwordx4 v164, s[24:25]
	s_add_i32 m0, s15, 0x400
	v_add_u32_e32 v165, s93, v232
	v_med3_i32 v165, v165, 0, s40
	v_lshl_or_b32 v165, v165, 7, v222
	global_load_lds_dwordx4 v165, s[24:25]
	s_waitcnt vmcnt(8)
	v_add_u32_e32 v154, s16, v225
	v_add_u32_e32 v155, s16, v226
	v_add_u32_e32 v156, s16, v227
	v_add_u32_e32 v157, s16, v228
	ds_read_b64_tr_b16 v[88:89], v154
	ds_read_b64_tr_b16 v[90:91], v155
	ds_read_b64_tr_b16 v[92:93], v156
	ds_read_b64_tr_b16 v[94:95], v157
	v_mfma_f32_16x16x32_bf16 v[68:71], v[202:205], v[80:83], 0
	v_mfma_f32_16x16x32_bf16 v[68:71], v[206:209], v[84:87], v[68:71]
	ds_read_b128 v[174:177], v197
	ds_read_b128 v[178:181], v198
	s_add_i32 s90, s76, 0x17c
	s_cmp_gt_i32 s90, s40
	s_cselect_b32 s96, 1, 0
	s_cmp_lt_i32 s76, 0x100
	s_cselect_b32 s96, 1, s96
	s_ashr_i32 s77, s76, 2
	s_sub_i32 s77, 64, s77
	s_sub_i32 s78, s40, s76
	s_ashr_i32 s78, s78, 2
	s_add_i32 s78, s78, 64
	v_cndmask_b32_e64 v0, v0, v230, s[52:53]
	v_cndmask_b32_e64 v32, v32, v230, s[62:63]
	v_cndmask_b32_e64 v1, v1, v230, s[56:57]
	v_cndmask_b32_e64 v33, v33, v230, s[64:65]
	v_cndmask_b32_e64 v2, v2, v230, s[58:59]
	v_cndmask_b32_e64 v34, v34, v230, s[70:71]
	v_cndmask_b32_e64 v3, v3, v230, s[60:61]
	v_cndmask_b32_e64 v35, v35, v230, s[72:73]
	s_cmp_eq_u32 s96, 0
	s_cbranch_scc1 .Latt_noedge_3
	v_sub_u32_e32 v200, s77, v229
	s_sub_i32 s91, s78, s77
	v_sub_u32_e32 v150, 0, v200
	v_sub_u32_e32 v151, 1, v200
	v_sub_u32_e32 v152, 2, v200
	v_sub_u32_e32 v153, 3, v200
	v_cmp_lt_u32_e64 s[94:95], s91, v150
	v_cmp_lt_u32_e64 s[86:87], s91, v151
	v_cmp_lt_u32_e64 s[0:1], s91, v152
	v_cmp_lt_u32_e64 s[2:3], s91, v153
	v_cndmask_b32_e64 v0, v0, v230, s[94:95]
	v_cndmask_b32_e64 v1, v1, v230, s[86:87]
	v_cndmask_b32_e64 v2, v2, v230, s[0:1]
	v_cndmask_b32_e64 v3, v3, v230, s[2:3]
	v_sub_u32_e32 v150, 16, v200
	v_sub_u32_e32 v151, 17, v200
	v_sub_u32_e32 v152, 18, v200
	v_sub_u32_e32 v153, 19, v200
	v_cmp_lt_u32_e64 s[94:95], s91, v150
	v_cmp_lt_u32_e64 s[86:87], s91, v151
	v_cmp_lt_u32_e64 s[0:1], s91, v152
	v_cmp_lt_u32_e64 s[2:3], s91, v153
	v_cndmask_b32_e64 v4, v4, v230, s[94:95]
	v_cndmask_b32_e64 v5, v5, v230, s[86:87]
	v_cndmask_b32_e64 v6, v6, v230, s[0:1]
	v_cndmask_b32_e64 v7, v7, v230, s[2:3]
	v_sub_u32_e32 v150, 32, v200
	v_sub_u32_e32 v151, 33, v200
	v_sub_u32_e32 v152, 34, v200
	v_sub_u32_e32 v153, 35, v200
	v_cmp_lt_u32_e64 s[94:95], s91, v150
	v_cmp_lt_u32_e64 s[86:87], s91, v151
	v_cmp_lt_u32_e64 s[0:1], s91, v152
	v_cmp_lt_u32_e64 s[2:3], s91, v153
	v_cndmask_b32_e64 v8, v8, v230, s[94:95]
	v_cndmask_b32_e64 v9, v9, v230, s[86:87]
	v_cndmask_b32_e64 v10, v10, v230, s[0:1]
	v_cndmask_b32_e64 v11, v11, v230, s[2:3]
	v_sub_u32_e32 v150, 48, v200
	v_sub_u32_e32 v151, 49, v200
	v_sub_u32_e32 v152, 50, v200
	v_sub_u32_e32 v153, 51, v200
	v_cmp_lt_u32_e64 s[94:95], s91, v150
	v_cmp_lt_u32_e64 s[86:87], s91, v151
	v_cmp_lt_u32_e64 s[0:1], s91, v152
	v_cmp_lt_u32_e64 s[2:3], s91, v153
	v_cndmask_b32_e64 v12, v12, v230, s[94:95]
	v_cndmask_b32_e64 v13, v13, v230, s[86:87]
	v_cndmask_b32_e64 v14, v14, v230, s[0:1]
	v_cndmask_b32_e64 v15, v15, v230, s[2:3]
	v_sub_u32_e32 v150, 64, v200
	v_sub_u32_e32 v151, 0x41, v200
	v_sub_u32_e32 v152, 0x42, v200
	v_sub_u32_e32 v153, 0x43, v200
	v_cmp_lt_u32_e64 s[94:95], s91, v150
	v_cmp_lt_u32_e64 s[86:87], s91, v151
	v_cmp_lt_u32_e64 s[0:1], s91, v152
	v_cmp_lt_u32_e64 s[2:3], s91, v153
	v_cndmask_b32_e64 v16, v16, v230, s[94:95]
	v_cndmask_b32_e64 v17, v17, v230, s[86:87]
	v_cndmask_b32_e64 v18, v18, v230, s[0:1]
	v_cndmask_b32_e64 v19, v19, v230, s[2:3]
	v_sub_u32_e32 v150, 0x50, v200
	v_sub_u32_e32 v151, 0x51, v200
	v_sub_u32_e32 v152, 0x52, v200
	v_sub_u32_e32 v153, 0x53, v200
	v_cmp_lt_u32_e64 s[94:95], s91, v150
	v_cmp_lt_u32_e64 s[86:87], s91, v151
	v_cmp_lt_u32_e64 s[0:1], s91, v152
	v_cmp_lt_u32_e64 s[2:3], s91, v153
	v_cndmask_b32_e64 v20, v20, v230, s[94:95]
	v_cndmask_b32_e64 v21, v21, v230, s[86:87]
	v_cndmask_b32_e64 v22, v22, v230, s[0:1]
	v_cndmask_b32_e64 v23, v23, v230, s[2:3]
	v_sub_u32_e32 v150, 0x60, v200
	v_sub_u32_e32 v151, 0x61, v200
	v_sub_u32_e32 v152, 0x62, v200
	v_sub_u32_e32 v153, 0x63, v200
	v_cmp_lt_u32_e64 s[94:95], s91, v150
	v_cmp_lt_u32_e64 s[86:87], s91, v151
	v_cmp_lt_u32_e64 s[0:1], s91, v152
	v_cmp_lt_u32_e64 s[2:3], s91, v153
	v_cndmask_b32_e64 v24, v24, v230, s[94:95]
	v_cndmask_b32_e64 v25, v25, v230, s[86:87]
	v_cndmask_b32_e64 v26, v26, v230, s[0:1]
	v_cndmask_b32_e64 v27, v27, v230, s[2:3]
	v_sub_u32_e32 v150, 0x70, v200
	v_sub_u32_e32 v151, 0x71, v200
	v_sub_u32_e32 v152, 0x72, v200
	v_sub_u32_e32 v153, 0x73, v200
	v_cmp_lt_u32_e64 s[94:95], s91, v150
	v_cmp_lt_u32_e64 s[86:87], s91, v151
	v_cmp_lt_u32_e64 s[0:1], s91, v152
	v_cmp_lt_u32_e64 s[2:3], s91, v153
	v_cndmask_b32_e64 v28, v28, v230, s[94:95]
	v_cndmask_b32_e64 v29, v29, v230, s[86:87]
	v_cndmask_b32_e64 v30, v30, v230, s[0:1]
	v_cndmask_b32_e64 v31, v31, v230, s[2:3]
	v_sub_u32_e32 v150, 0x80, v200
	v_sub_u32_e32 v151, 0x81, v200
	v_sub_u32_e32 v152, 0x82, v200
	v_sub_u32_e32 v153, 0x83, v200
	v_cmp_lt_u32_e64 s[94:95], s91, v150
	v_cmp_lt_u32_e64 s[86:87], s91, v151
	v_cmp_lt_u32_e64 s[0:1], s91, v152
	v_cmp_lt_u32_e64 s[2:3], s91, v153
	v_cndmask_b32_e64 v32, v32, v230, s[94:95]
	v_cndmask_b32_e64 v33, v33, v230, s[86:87]
	v_cndmask_b32_e64 v34, v34, v230, s[0:1]
	v_cndmask_b32_e64 v35, v35, v230, s[2:3]
